# SWA prompt row-tile loop: QK and PV LDS fragment reads software-pipelined (counted lgkmcnt), Q loads as global_load
# baseline (speedup 1.0000x reference)
.LBB0_132:
	s_and_b32 s7, s0, 0x70
	v_or_b32_e32 v67, s7, v65
	v_readlane_b32 s7, v255, 10
	s_ashr_i32 s6, s71, 3
	v_mov_b64_e32 v[0:1], s[10:11]
	v_or_b32_e32 v68, s7, v67
	v_readlane_b32 s7, v255, 12
	s_add_i32 s8, s6, s7
	v_mad_i64_i32 v[0:1], s[6:7], v68, s9, v[0:1]
	s_lshl_b32 s6, s8, 6
	s_ashr_i32 s7, s6, 31
	s_lshl_b64 s[6:7], s[6:7], 1
	v_lshl_add_u64 v[0:1], v[0:1], 0, s[6:7]
	v_lshlrev_b32_e32 v152, 1, v64
	v_lshl_add_u64 v[4:5], v[0:1], 0, v[152:153]
	global_load_dwordx4 v[0:3], v[4:5], off
	global_load_dwordx4 v[134:137], v[4:5], off offset:64
	ds_read_b128 v[194:197], v120
	ds_read_b128 v[198:201], v120 offset:64
	ds_read_b128 v[202:205], v121
	ds_read_b128 v[206:209], v121 offset:64
	ds_read_b128 v[210:213], v122
	ds_read_b128 v[214:217], v122 offset:64
	ds_read_b128 v[218:221], v123
	ds_read_b128 v[222:225], v123 offset:64
	v_ashrrev_i32_e32 v69, 31, v68
	s_waitcnt vmcnt(0)
	s_waitcnt lgkmcnt(6)
	v_mfma_f32_16x16x32_bf16 v[140:143], v[194:197], v[0:3], 0
	v_mfma_f32_16x16x32_bf16 v[140:143], v[198:201], v[134:137], v[140:143]
	ds_read_b128 v[194:197], v124
	ds_read_b128 v[198:201], v124 offset:64
	s_waitcnt lgkmcnt(6)
	v_mfma_f32_16x16x32_bf16 v[32:35], v[202:205], v[0:3], 0
	v_mfma_f32_16x16x32_bf16 v[32:35], v[206:209], v[134:137], v[32:35]
	ds_read_b128 v[202:205], v125
	ds_read_b128 v[206:209], v125 offset:64
	s_waitcnt lgkmcnt(6)
	v_mfma_f32_16x16x32_bf16 v[24:27], v[210:213], v[0:3], 0
	v_mfma_f32_16x16x32_bf16 v[24:27], v[214:217], v[134:137], v[24:27]
	ds_read_b128 v[210:213], v126
	ds_read_b128 v[214:217], v126 offset:64
	s_waitcnt lgkmcnt(6)
	v_mfma_f32_16x16x32_bf16 v[28:31], v[218:221], v[0:3], 0
	v_mfma_f32_16x16x32_bf16 v[28:31], v[222:225], v[134:137], v[28:31]
	ds_read_b128 v[218:221], v127
	ds_read_b128 v[222:225], v127 offset:64
	s_waitcnt lgkmcnt(6)
	v_mfma_f32_16x16x32_bf16 v[16:19], v[194:197], v[0:3], 0
	v_mfma_f32_16x16x32_bf16 v[16:19], v[198:201], v[134:137], v[16:19]
	ds_read_b128 v[194:197], v128
	ds_read_b128 v[198:201], v128 offset:64
	s_waitcnt lgkmcnt(6)
	v_mfma_f32_16x16x32_bf16 v[20:23], v[202:205], v[0:3], 0
	v_mfma_f32_16x16x32_bf16 v[20:23], v[206:209], v[134:137], v[20:23]
	ds_read_b128 v[202:205], v129
	ds_read_b128 v[206:209], v129 offset:64
	s_waitcnt lgkmcnt(6)
	v_mfma_f32_16x16x32_bf16 v[8:11], v[210:213], v[0:3], 0
	v_mfma_f32_16x16x32_bf16 v[8:11], v[214:217], v[134:137], v[8:11]
	s_waitcnt lgkmcnt(4)
	v_mfma_f32_16x16x32_bf16 v[12:15], v[218:221], v[0:3], 0
	v_mfma_f32_16x16x32_bf16 v[12:15], v[222:225], v[134:137], v[12:15]
	s_waitcnt lgkmcnt(2)
	v_mfma_f32_16x16x32_bf16 v[4:7], v[194:197], v[0:3], 0
	v_mfma_f32_16x16x32_bf16 v[4:7], v[198:201], v[134:137], v[4:7]
	s_waitcnt lgkmcnt(0)
	v_mfma_f32_16x16x32_bf16 v[0:3], v[202:205], v[0:3], 0
	v_mfma_f32_16x16x32_bf16 v[0:3], v[206:209], v[134:137], v[0:3]
	v_or_b32_e32 v138, 0x80, v67
	v_cmp_gt_u32_e32 vcc, v80, v67
	v_cmp_le_u32_e64 s[12:13], v80, v138
	s_and_b64 s[12:13], vcc, s[12:13]
	v_readlane_b32 vcc_lo, v255, 14
	v_readlane_b32 vcc_hi, v255, 15
	s_and_b64 vcc, vcc, s[12:13]
	v_mul_f32_e32 v134, 0x3e000000, v140
	v_cndmask_b32_e32 v134, v187, v134, vcc
	v_cmp_ge_u32_e32 vcc, v80, v67
	v_cmp_lt_u32_e64 s[12:13], v80, v138
	s_and_b64 s[12:13], vcc, s[12:13]
	v_readlane_b32 vcc_lo, v255, 16
	v_readlane_b32 vcc_hi, v255, 17
	s_and_b64 vcc, vcc, s[12:13]
	v_mul_f32_e32 v135, 0x3e000000, v141
	v_cndmask_b32_e32 v135, v187, v135, vcc
	v_cmp_gt_u32_e32 vcc, v82, v67
	v_cmp_le_u32_e64 s[12:13], v82, v138
	s_and_b64 s[12:13], vcc, s[12:13]
	v_readlane_b32 vcc_lo, v255, 18
	v_readlane_b32 vcc_hi, v255, 19
	s_and_b64 vcc, vcc, s[12:13]
	v_mul_f32_e32 v136, 0x3e000000, v142
	v_cndmask_b32_e32 v136, v187, v136, vcc
	v_cmp_gt_u32_e32 vcc, v83, v67
	v_cmp_le_u32_e64 s[12:13], v83, v138
	s_and_b64 s[12:13], vcc, s[12:13]
	v_readlane_b32 vcc_lo, v255, 20
	v_readlane_b32 vcc_hi, v255, 21
	s_and_b64 vcc, vcc, s[12:13]
	v_mul_f32_e32 v137, 0x3e000000, v143
	v_cndmask_b32_e32 v137, v187, v137, vcc
	v_cmp_gt_u32_e32 vcc, v84, v67
	v_cmp_le_u32_e64 s[12:13], v84, v138
	s_and_b64 s[12:13], vcc, s[12:13]
	v_readlane_b32 vcc_lo, v255, 22
	v_readlane_b32 vcc_hi, v255, 23
	s_and_b64 vcc, vcc, s[12:13]
	v_mul_f32_e32 v32, 0x3e000000, v32
	v_cndmask_b32_e32 v32, v187, v32, vcc
	v_cmp_ge_u32_e32 vcc, v84, v67
	v_cmp_lt_u32_e64 s[12:13], v84, v138
	s_and_b64 s[12:13], vcc, s[12:13]
	v_readlane_b32 vcc_lo, v255, 24
	v_readlane_b32 vcc_hi, v255, 25
	s_and_b64 vcc, vcc, s[12:13]
	v_mul_f32_e32 v33, 0x3e000000, v33
	v_cndmask_b32_e32 v33, v187, v33, vcc
	v_cmp_gt_u32_e32 vcc, v86, v67
	v_cmp_le_u32_e64 s[12:13], v86, v138
	s_and_b64 s[12:13], vcc, s[12:13]
	v_readlane_b32 vcc_lo, v255, 26
	v_readlane_b32 vcc_hi, v255, 27
	s_and_b64 vcc, vcc, s[12:13]
	v_mul_f32_e32 v34, 0x3e000000, v34
	v_cndmask_b32_e32 v34, v187, v34, vcc
	v_cmp_gt_u32_e32 vcc, v87, v67
	v_cmp_le_u32_e64 s[12:13], v87, v138
	s_and_b64 s[12:13], vcc, s[12:13]
	v_readlane_b32 vcc_lo, v255, 28
	v_readlane_b32 vcc_hi, v255, 29
	s_and_b64 vcc, vcc, s[12:13]
	v_mul_f32_e32 v35, 0x3e000000, v35
	v_cndmask_b32_e32 v35, v187, v35, vcc
	v_cmp_gt_u32_e32 vcc, v88, v67
	v_cmp_le_u32_e64 s[12:13], v88, v138
	s_and_b64 s[12:13], vcc, s[12:13]
	v_readlane_b32 vcc_lo, v255, 30
	v_readlane_b32 vcc_hi, v255, 31
	s_and_b64 vcc, vcc, s[12:13]
	v_mul_f32_e32 v24, 0x3e000000, v24
	v_cndmask_b32_e32 v24, v187, v24, vcc
	v_cmp_ge_u32_e32 vcc, v88, v67
	v_cmp_lt_u32_e64 s[12:13], v88, v138
	s_and_b64 s[12:13], vcc, s[12:13]
	v_readlane_b32 vcc_lo, v255, 32
	v_readlane_b32 vcc_hi, v255, 33
	s_and_b64 vcc, vcc, s[12:13]
	v_mul_f32_e32 v25, 0x3e000000, v25
	v_cndmask_b32_e32 v25, v187, v25, vcc
	v_cmp_gt_u32_e32 vcc, v90, v67
	v_cmp_le_u32_e64 s[12:13], v90, v138
	s_and_b64 s[12:13], vcc, s[12:13]
	s_and_b64 vcc, s[52:53], s[12:13]
	v_mul_f32_e32 v26, 0x3e000000, v26
	v_cndmask_b32_e32 v26, v187, v26, vcc
	v_cmp_gt_u32_e32 vcc, v91, v67
	v_cmp_le_u32_e64 s[12:13], v91, v138
	s_and_b64 s[12:13], vcc, s[12:13]
	s_and_b64 vcc, s[54:55], s[12:13]
	v_mul_f32_e32 v27, 0x3e000000, v27
	v_cndmask_b32_e32 v27, v187, v27, vcc
	v_cmp_gt_u32_e32 vcc, v92, v67
	v_cmp_le_u32_e64 s[12:13], v92, v138
	s_and_b64 s[12:13], vcc, s[12:13]
	s_and_b64 vcc, s[14:15], s[12:13]
	v_mul_f32_e32 v28, 0x3e000000, v28
	v_cndmask_b32_e32 v28, v187, v28, vcc
	v_cmp_ge_u32_e32 vcc, v92, v67
	v_cmp_lt_u32_e64 s[12:13], v92, v138
	s_and_b64 s[12:13], vcc, s[12:13]
	s_and_b64 vcc, s[16:17], s[12:13]
	v_mul_f32_e32 v29, 0x3e000000, v29
	v_cndmask_b32_e32 v29, v187, v29, vcc
	v_cmp_gt_u32_e32 vcc, v94, v67
	v_cmp_le_u32_e64 s[12:13], v94, v138
	s_and_b64 s[12:13], vcc, s[12:13]
	s_and_b64 vcc, s[20:21], s[12:13]
	v_mul_f32_e32 v30, 0x3e000000, v30
	v_cndmask_b32_e32 v30, v187, v30, vcc
	v_cmp_gt_u32_e32 vcc, v95, v67
	v_cmp_le_u32_e64 s[12:13], v95, v138
	s_and_b64 s[12:13], vcc, s[12:13]
	s_and_b64 vcc, s[22:23], s[12:13]
	v_mul_f32_e32 v31, 0x3e000000, v31
	v_cndmask_b32_e32 v31, v187, v31, vcc
	v_cmp_gt_u32_e32 vcc, v96, v67
	v_cmp_le_u32_e64 s[12:13], v96, v138
	s_and_b64 s[12:13], vcc, s[12:13]
	s_and_b64 vcc, s[64:65], s[12:13]
	v_mul_f32_e32 v16, 0x3e000000, v16
	v_cndmask_b32_e32 v16, v187, v16, vcc
	v_cmp_ge_u32_e32 vcc, v96, v67
	v_cmp_lt_u32_e64 s[12:13], v96, v138
	s_and_b64 s[12:13], vcc, s[12:13]
	s_and_b64 vcc, s[66:67], s[12:13]
	v_mul_f32_e32 v17, 0x3e000000, v17
	v_cndmask_b32_e32 v17, v187, v17, vcc
	v_cmp_gt_u32_e32 vcc, v98, v67
	v_cmp_le_u32_e64 s[12:13], v98, v138
	s_and_b64 s[12:13], vcc, s[12:13]
	s_and_b64 vcc, s[68:69], s[12:13]
	v_mul_f32_e32 v18, 0x3e000000, v18
	v_cndmask_b32_e32 v18, v187, v18, vcc
	v_cmp_gt_u32_e32 vcc, v99, v67
	v_cmp_le_u32_e64 s[12:13], v99, v138
	s_and_b64 s[12:13], vcc, s[12:13]
	s_and_b64 vcc, s[24:25], s[12:13]
	v_mul_f32_e32 v19, 0x3e000000, v19
	v_cndmask_b32_e32 v19, v187, v19, vcc
	v_cmp_gt_u32_e32 vcc, v100, v67
	v_cmp_le_u32_e64 s[12:13], v100, v138
	s_and_b64 s[12:13], vcc, s[12:13]
	s_and_b64 vcc, s[72:73], s[12:13]
	v_mul_f32_e32 v20, 0x3e000000, v20
	v_cndmask_b32_e32 v20, v187, v20, vcc
	v_cmp_ge_u32_e32 vcc, v100, v67
	v_cmp_lt_u32_e64 s[12:13], v100, v138
	s_and_b64 s[12:13], vcc, s[12:13]
	s_and_b64 vcc, s[74:75], s[12:13]
	v_mul_f32_e32 v21, 0x3e000000, v21
	v_cndmask_b32_e32 v21, v187, v21, vcc
	v_cmp_gt_u32_e32 vcc, v102, v67
	v_cmp_le_u32_e64 s[12:13], v102, v138
	s_and_b64 s[12:13], vcc, s[12:13]
	s_and_b64 vcc, s[76:77], s[12:13]
	v_mul_f32_e32 v22, 0x3e000000, v22
	v_cndmask_b32_e32 v22, v187, v22, vcc
	v_cmp_gt_u32_e32 vcc, v103, v67
	v_cmp_le_u32_e64 s[12:13], v103, v138
	s_and_b64 s[12:13], vcc, s[12:13]
	s_and_b64 vcc, s[78:79], s[12:13]
	v_mul_f32_e32 v23, 0x3e000000, v23
	v_cndmask_b32_e32 v23, v187, v23, vcc
	v_cmp_gt_u32_e32 vcc, v104, v67
	v_cmp_le_u32_e64 s[12:13], v104, v138
	s_and_b64 s[12:13], vcc, s[12:13]
	s_and_b64 vcc, s[80:81], s[12:13]
	v_mul_f32_e32 v8, 0x3e000000, v8
	v_cndmask_b32_e32 v8, v187, v8, vcc
	v_cmp_ge_u32_e32 vcc, v104, v67
	v_cmp_lt_u32_e64 s[12:13], v104, v138
	s_and_b64 s[12:13], vcc, s[12:13]
	s_and_b64 vcc, s[82:83], s[12:13]
	v_mul_f32_e32 v9, 0x3e000000, v9
	v_cndmask_b32_e32 v9, v187, v9, vcc
	v_cmp_gt_u32_e32 vcc, v106, v67
	v_cmp_le_u32_e64 s[12:13], v106, v138
	s_and_b64 s[12:13], vcc, s[12:13]
	s_and_b64 vcc, s[84:85], s[12:13]
	v_mul_f32_e32 v10, 0x3e000000, v10
	v_cndmask_b32_e32 v10, v187, v10, vcc
	v_cmp_gt_u32_e32 vcc, v107, v67
	v_cmp_le_u32_e64 s[12:13], v107, v138
	s_and_b64 s[12:13], vcc, s[12:13]
	s_and_b64 vcc, s[86:87], s[12:13]
	v_mul_f32_e32 v11, 0x3e000000, v11
	v_cndmask_b32_e32 v11, v187, v11, vcc
	v_cmp_gt_u32_e32 vcc, v108, v67
	v_cmp_le_u32_e64 s[12:13], v108, v138
	s_and_b64 s[12:13], vcc, s[12:13]
	s_and_b64 vcc, s[88:89], s[12:13]
	v_mul_f32_e32 v12, 0x3e000000, v12
	v_cndmask_b32_e32 v12, v187, v12, vcc
	v_cmp_ge_u32_e32 vcc, v108, v67
	v_cmp_lt_u32_e64 s[12:13], v108, v138
	s_and_b64 s[12:13], vcc, s[12:13]
	s_and_b64 vcc, s[90:91], s[12:13]
	v_mul_f32_e32 v13, 0x3e000000, v13
	v_cndmask_b32_e32 v13, v187, v13, vcc
	v_cmp_gt_u32_e32 vcc, v110, v67
	v_cmp_le_u32_e64 s[12:13], v110, v138
	s_and_b64 s[12:13], vcc, s[12:13]
	s_and_b64 vcc, s[92:93], s[12:13]
	v_mul_f32_e32 v14, 0x3e000000, v14
	v_cndmask_b32_e32 v14, v187, v14, vcc
	v_cmp_gt_u32_e32 vcc, v111, v67
	v_cmp_le_u32_e64 s[12:13], v111, v138
	s_and_b64 s[12:13], vcc, s[12:13]
	s_ashr_i32 s9, s8, 31
	s_and_b64 vcc, s[94:95], s[12:13]
	s_lshl_b64 s[8:9], s[8:9], 2
	s_add_u32 s8, s18, s8
	s_addc_u32 s9, s19, s9
	global_load_dword v141, v153, s[8:9]
	v_mul_f32_e32 v15, 0x3e000000, v15
	v_cndmask_b32_e32 v15, v187, v15, vcc
	v_mul_f32_e32 v4, 0x3e000000, v4
	v_cmp_le_u32_e32 vcc, v112, v138
	v_mul_f32_e32 v5, 0x3e000000, v5
	v_add_u32_e32 v139, 0x7e, v67
	v_cndmask_b32_e32 v4, v187, v4, vcc
	v_cmp_lt_u32_e32 vcc, v112, v138
	v_mul_f32_e32 v6, 0x3e000000, v6
	v_add_u32_e32 v67, 0x7d, v67
	v_cndmask_b32_e32 v5, v187, v5, vcc
	v_cmp_le_u32_e32 vcc, v112, v139
	v_mul_f32_e32 v7, 0x3e000000, v7
	v_mul_f32_e32 v0, 0x3e000000, v0
	v_cndmask_b32_e32 v6, v187, v6, vcc
	v_cmp_le_u32_e32 vcc, v112, v67
	s_addk_i32 s0, 0x80
	s_nop 0
	v_cndmask_b32_e32 v7, v187, v7, vcc
	v_cmp_le_u32_e32 vcc, v113, v138
	s_nop 1
	v_cndmask_b32_e32 v140, v187, v0, vcc
	v_cmp_lt_u32_e32 vcc, v113, v138
	v_mul_f32_e32 v0, 0x3e000000, v1
	v_max_f32_e32 v1, v34, v35
	v_cndmask_b32_e32 v138, v187, v0, vcc
	v_mul_f32_e32 v0, 0x3e000000, v2
	v_cmp_le_u32_e32 vcc, v113, v139
	v_max3_f32 v1, v32, v33, v1
	v_max_f32_e32 v2, v30, v31
	v_cndmask_b32_e32 v139, v187, v0, vcc
	v_mul_f32_e32 v0, 0x3e000000, v3
	v_cmp_le_u32_e32 vcc, v113, v67
	v_max3_f32 v2, v28, v29, v2
	s_nop 0
	v_cndmask_b32_e32 v67, v187, v0, vcc
	v_max_f32_e32 v0, v136, v137
	v_max3_f32 v0, v134, v135, v0
	s_waitcnt vmcnt(0)
	v_max3_f32 v0, v141, v0, v1
	v_max_f32_e32 v1, v26, v27
	v_max3_f32 v1, v24, v25, v1
	v_max3_f32 v0, v0, v1, v2
	v_max_f32_e32 v1, v18, v19
	v_max_f32_e32 v2, v22, v23
	v_max3_f32 v1, v16, v17, v1
	v_max3_f32 v2, v20, v21, v2
	v_max3_f32 v0, v0, v1, v2
	v_max_f32_e32 v1, v10, v11
	v_max_f32_e32 v2, v14, v15
	v_max3_f32 v1, v8, v9, v1
	v_max3_f32 v2, v12, v13, v2
	v_max3_f32 v0, v0, v1, v2
	v_max_f32_e32 v1, v6, v7
	v_max_f32_e32 v2, v139, v67
	v_max3_f32 v1, v4, v5, v1
	v_max3_f32 v2, v140, v138, v2
	v_max3_f32 v0, v0, v1, v2
	ds_bpermute_b32 v1, v132, v0
	s_waitcnt lgkmcnt(0)
	v_max_f32_e32 v1, v1, v1
	v_max_f32_e32 v0, v0, v1
	ds_bpermute_b32 v1, v133, v0
	s_waitcnt lgkmcnt(0)
	v_max_f32_e32 v1, v1, v1
	v_max_f32_e32 v142, v0, v1
	v_sub_f32_e32 v0, v134, v142
	v_mul_f32_e32 v0, 0x3fb8aa3b, v0
	v_sub_f32_e32 v2, v135, v142
	v_exp_f32_e32 v0, v0
	v_mul_f32_e32 v2, 0x3fb8aa3b, v2
	v_exp_f32_e32 v2, v2
	v_sub_f32_e32 v3, v136, v142
	v_add_f32_e32 v1, 0, v0
	v_mul_f32_e32 v3, 0x3fb8aa3b, v3
	v_sub_f32_e32 v134, v137, v142
	v_add_f32_e32 v1, v2, v1
	v_exp_f32_e32 v3, v3
	v_mul_f32_e32 v134, 0x3fb8aa3b, v134
	v_cvt_pk_bf16_f32 v0, v0, v2
	v_sub_f32_e32 v2, v32, v142
	v_exp_f32_e32 v134, v134
	v_mul_f32_e32 v2, 0x3fb8aa3b, v2
	v_sub_f32_e32 v32, v33, v142
	v_exp_f32_e32 v2, v2
	v_mul_f32_e32 v32, 0x3fb8aa3b, v32
	v_sub_f32_e32 v33, v34, v142
	v_exp_f32_e32 v32, v32
	v_mul_f32_e32 v33, 0x3fb8aa3b, v33
	v_sub_f32_e32 v34, v35, v142
	v_add_f32_e32 v1, v3, v1
	v_exp_f32_e32 v33, v33
	v_mul_f32_e32 v34, 0x3fb8aa3b, v34
	v_add_f32_e32 v135, v134, v1
	v_exp_f32_e32 v34, v34
	v_cvt_pk_bf16_f32 v1, v3, v134
	v_add_f32_e32 v3, v2, v135
	v_add_f32_e32 v3, v32, v3
	v_add_f32_e32 v3, v33, v3
	v_add_u32_e32 v134, v79, v64
	v_add_f32_e32 v35, v34, v3
	v_cvt_pk_bf16_f32 v2, v2, v32
	v_cvt_pk_bf16_f32 v3, v33, v34
	ds_write2_b64 v134, v[0:1], v[2:3] offset1:4
	v_sub_f32_e32 v0, v24, v142
	v_mul_f32_e32 v0, 0x3fb8aa3b, v0
	v_sub_f32_e32 v2, v25, v142
	v_exp_f32_e32 v0, v0
	v_mul_f32_e32 v2, 0x3fb8aa3b, v2
	v_exp_f32_e32 v2, v2
	v_sub_f32_e32 v3, v26, v142
	v_add_f32_e32 v1, v0, v35
	v_mul_f32_e32 v3, 0x3fb8aa3b, v3
	v_sub_f32_e32 v24, v27, v142
	v_add_f32_e32 v1, v2, v1
	v_exp_f32_e32 v3, v3
	v_mul_f32_e32 v24, 0x3fb8aa3b, v24
	v_cvt_pk_bf16_f32 v0, v0, v2
	v_sub_f32_e32 v2, v28, v142
	v_exp_f32_e32 v24, v24
	v_mul_f32_e32 v2, 0x3fb8aa3b, v2
	v_exp_f32_e32 v2, v2
	v_add_f32_e32 v1, v3, v1
	v_add_f32_e32 v25, v24, v1
	v_cvt_pk_bf16_f32 v1, v3, v24
	v_sub_f32_e32 v24, v29, v142
	v_add_f32_e32 v3, v2, v25
	v_mul_f32_e32 v24, 0x3fb8aa3b, v24
	v_sub_f32_e32 v25, v30, v142
	v_exp_f32_e32 v24, v24
	v_mul_f32_e32 v25, 0x3fb8aa3b, v25
	v_sub_f32_e32 v26, v31, v142
	v_exp_f32_e32 v25, v25
	v_mul_f32_e32 v26, 0x3fb8aa3b, v26
	v_exp_f32_e32 v26, v26
	v_add_f32_e32 v3, v24, v3
	v_add_f32_e32 v3, v25, v3
	v_cvt_pk_bf16_f32 v2, v2, v24
	v_add_f32_e32 v27, v26, v3
	v_cvt_pk_bf16_f32 v3, v25, v26
	ds_write2_b64 v134, v[0:1], v[2:3] offset0:8 offset1:12
	v_sub_f32_e32 v0, v16, v142
	v_mul_f32_e32 v0, 0x3fb8aa3b, v0
	v_sub_f32_e32 v2, v17, v142
	v_exp_f32_e32 v0, v0
	v_mul_f32_e32 v2, 0x3fb8aa3b, v2
	v_exp_f32_e32 v2, v2
	v_sub_f32_e32 v3, v18, v142
	v_add_f32_e32 v1, v0, v27
	v_mul_f32_e32 v3, 0x3fb8aa3b, v3
	v_sub_f32_e32 v16, v19, v142
	v_add_f32_e32 v1, v2, v1
	v_exp_f32_e32 v3, v3
	v_mul_f32_e32 v16, 0x3fb8aa3b, v16
	v_cvt_pk_bf16_f32 v0, v0, v2
	v_sub_f32_e32 v2, v20, v142
	v_exp_f32_e32 v16, v16
	v_mul_f32_e32 v2, 0x3fb8aa3b, v2
	v_exp_f32_e32 v2, v2
	v_add_f32_e32 v1, v3, v1
	v_add_f32_e32 v17, v16, v1
	v_cvt_pk_bf16_f32 v1, v3, v16
	v_sub_f32_e32 v16, v21, v142
	v_add_f32_e32 v3, v2, v17
	v_mul_f32_e32 v16, 0x3fb8aa3b, v16
	v_sub_f32_e32 v17, v22, v142
	v_exp_f32_e32 v16, v16
	v_mul_f32_e32 v17, 0x3fb8aa3b, v17
	v_sub_f32_e32 v18, v23, v142
	v_exp_f32_e32 v17, v17
	v_mul_f32_e32 v18, 0x3fb8aa3b, v18
	v_exp_f32_e32 v18, v18
	v_add_f32_e32 v3, v16, v3
	v_add_f32_e32 v3, v17, v3
	v_cvt_pk_bf16_f32 v2, v2, v16
	v_add_f32_e32 v19, v18, v3
	v_cvt_pk_bf16_f32 v3, v17, v18
	ds_write2_b64 v134, v[0:1], v[2:3] offset0:16 offset1:20
	v_sub_f32_e32 v0, v8, v142
	v_mul_f32_e32 v0, 0x3fb8aa3b, v0
	v_sub_f32_e32 v2, v9, v142
	v_exp_f32_e32 v0, v0
	v_mul_f32_e32 v2, 0x3fb8aa3b, v2
	v_exp_f32_e32 v2, v2
	v_sub_f32_e32 v3, v10, v142
	v_add_f32_e32 v1, v0, v19
	v_mul_f32_e32 v3, 0x3fb8aa3b, v3
	v_sub_f32_e32 v8, v11, v142
	v_add_f32_e32 v1, v2, v1
	v_exp_f32_e32 v3, v3
	v_mul_f32_e32 v8, 0x3fb8aa3b, v8
	v_cvt_pk_bf16_f32 v0, v0, v2
	v_sub_f32_e32 v2, v12, v142
	v_exp_f32_e32 v8, v8
	v_mul_f32_e32 v2, 0x3fb8aa3b, v2
	v_exp_f32_e32 v2, v2
	v_add_f32_e32 v1, v3, v1
	v_add_f32_e32 v9, v8, v1
	v_cvt_pk_bf16_f32 v1, v3, v8
	v_sub_f32_e32 v8, v13, v142
	v_add_f32_e32 v3, v2, v9
	v_mul_f32_e32 v8, 0x3fb8aa3b, v8
	v_sub_f32_e32 v9, v14, v142
	v_exp_f32_e32 v8, v8
	v_mul_f32_e32 v9, 0x3fb8aa3b, v9
	v_sub_f32_e32 v10, v15, v142
	v_exp_f32_e32 v9, v9
	v_mul_f32_e32 v10, 0x3fb8aa3b, v10
	v_exp_f32_e32 v10, v10
	v_add_f32_e32 v3, v8, v3
	v_add_f32_e32 v3, v9, v3
	v_cvt_pk_bf16_f32 v2, v2, v8
	v_add_f32_e32 v11, v10, v3
	v_cvt_pk_bf16_f32 v3, v9, v10
	ds_write2_b64 v134, v[0:1], v[2:3] offset0:24 offset1:28
	v_sub_f32_e32 v0, v4, v142
	v_mul_f32_e32 v0, 0x3fb8aa3b, v0
	v_sub_f32_e32 v2, v5, v142
	v_exp_f32_e32 v0, v0
	v_mul_f32_e32 v2, 0x3fb8aa3b, v2
	v_exp_f32_e32 v2, v2
	v_sub_f32_e32 v3, v6, v142
	v_add_f32_e32 v1, v0, v11
	v_mul_f32_e32 v3, 0x3fb8aa3b, v3
	v_sub_f32_e32 v4, v7, v142
	v_add_f32_e32 v1, v2, v1
	v_exp_f32_e32 v3, v3
	v_mul_f32_e32 v4, 0x3fb8aa3b, v4
	v_cvt_pk_bf16_f32 v0, v0, v2
	v_sub_f32_e32 v2, v140, v142
	v_exp_f32_e32 v4, v4
	v_mul_f32_e32 v2, 0x3fb8aa3b, v2
	v_exp_f32_e32 v2, v2
	v_add_f32_e32 v1, v3, v1
	v_add_f32_e32 v5, v4, v1
	v_cvt_pk_bf16_f32 v1, v3, v4
	v_sub_f32_e32 v4, v138, v142
	v_add_f32_e32 v3, v2, v5
	v_mul_f32_e32 v4, 0x3fb8aa3b, v4
	v_sub_f32_e32 v5, v139, v142
	v_exp_f32_e32 v4, v4
	v_mul_f32_e32 v5, 0x3fb8aa3b, v5
	v_sub_f32_e32 v6, v67, v142
	v_exp_f32_e32 v5, v5
	v_mul_f32_e32 v6, 0x3fb8aa3b, v6
	v_exp_f32_e32 v6, v6
	v_add_f32_e32 v3, v4, v3
	v_add_f32_e32 v3, v5, v3
	v_cvt_pk_bf16_f32 v2, v2, v4
	v_add_f32_e32 v7, v6, v3
	v_cvt_pk_bf16_f32 v3, v5, v6
	ds_write2_b64 v134, v[0:1], v[2:3] offset0:32 offset1:36
	ds_bpermute_b32 v0, v132, v7
	s_waitcnt lgkmcnt(0)
	v_add_u32_e32 v25, v79, v78
	v_mov_b32_e32 v67, v153
	s_waitcnt lgkmcnt(0)
	v_add_f32_e32 v0, v7, v0
	ds_bpermute_b32 v1, v133, v0
	s_waitcnt lgkmcnt(0)
	v_add_f32_e32 v0, v0, v1
	v_sub_f32_e32 v1, v141, v142
	v_mul_f32_e32 v1, 0x3fb8aa3b, v1
	v_exp_f32_e32 v1, v1
	s_nop 0
	v_add_f32_e32 v24, v1, v0
	ds_read_b128 v[194:197], v25
	ds_read_b128 v[214:217], v130 offset:36864
	ds_read_b128 v[218:221], v130 offset:45312
	ds_read_b128 v[222:225], v130 offset:53760
	ds_read_b128 v[226:229], v131 offset:36864
	ds_read_b128 v[198:201], v25 offset:64
	ds_read_b128 v[230:233], v130 offset:36928
	ds_read_b128 v[234:237], v130 offset:45376
	ds_read_b128 v[238:241], v130 offset:53824
	ds_read_b128 v[242:245], v131 offset:36928
	s_waitcnt lgkmcnt(5)
	v_mfma_f32_16x16x32_bf16 v[12:15], v[214:217], v[194:197], 0
	v_mfma_f32_16x16x32_bf16 v[8:11], v[218:221], v[194:197], 0
	v_mfma_f32_16x16x32_bf16 v[4:7], v[222:225], v[194:197], 0
	v_mfma_f32_16x16x32_bf16 v[0:3], v[226:229], v[194:197], 0
	ds_read_b128 v[202:205], v25 offset:128
	ds_read_b128 v[214:217], v130 offset:36992
	ds_read_b128 v[218:221], v130 offset:45440
	ds_read_b128 v[222:225], v130 offset:53888
	ds_read_b128 v[226:229], v131 offset:36992
	s_waitcnt lgkmcnt(5)
	v_mfma_f32_16x16x32_bf16 v[12:15], v[230:233], v[198:201], v[12:15]
	v_mfma_f32_16x16x32_bf16 v[8:11], v[234:237], v[198:201], v[8:11]
	v_mfma_f32_16x16x32_bf16 v[4:7], v[238:241], v[198:201], v[4:7]
	v_mfma_f32_16x16x32_bf16 v[0:3], v[242:245], v[198:201], v[0:3]
	ds_read_b128 v[206:209], v25 offset:192
	ds_read_b128 v[230:233], v130 offset:37056
	ds_read_b128 v[234:237], v130 offset:45504
	ds_read_b128 v[238:241], v130 offset:53952
	ds_read_b128 v[242:245], v131 offset:37056
	s_waitcnt lgkmcnt(5)
	v_mfma_f32_16x16x32_bf16 v[12:15], v[214:217], v[202:205], v[12:15]
	v_mfma_f32_16x16x32_bf16 v[8:11], v[218:221], v[202:205], v[8:11]
	v_mfma_f32_16x16x32_bf16 v[4:7], v[222:225], v[202:205], v[4:7]
	v_mfma_f32_16x16x32_bf16 v[0:3], v[226:229], v[202:205], v[0:3]
	ds_read_b128 v[210:213], v25 offset:256
	ds_read_b128 v[214:217], v130 offset:37120
	ds_read_b128 v[218:221], v130 offset:45568
	ds_read_b128 v[222:225], v130 offset:54016
	ds_read_b128 v[226:229], v131 offset:37120
	s_waitcnt lgkmcnt(5)
	v_mfma_f32_16x16x32_bf16 v[12:15], v[230:233], v[206:209], v[12:15]
	v_mfma_f32_16x16x32_bf16 v[8:11], v[234:237], v[206:209], v[8:11]
	v_mfma_f32_16x16x32_bf16 v[4:7], v[238:241], v[206:209], v[4:7]
	v_mfma_f32_16x16x32_bf16 v[0:3], v[242:245], v[206:209], v[0:3]
	s_waitcnt lgkmcnt(0)
	v_mfma_f32_16x16x32_bf16 v[12:15], v[214:217], v[210:213], v[12:15]
	v_mfma_f32_16x16x32_bf16 v[8:11], v[218:221], v[210:213], v[8:11]
	v_mfma_f32_16x16x32_bf16 v[4:7], v[222:225], v[210:213], v[4:7]
	v_mfma_f32_16x16x32_bf16 v[0:3], v[226:229], v[210:213], v[0:3]
	v_div_scale_f32 v16, s[8:9], v24, v24, 1.0
	v_rcp_f32_e32 v17, v16
	s_movk_i32 s9, 0xc00
	v_fma_f32 v18, -v16, v17, 1.0
	v_fmac_f32_e32 v17, v18, v17
	v_div_scale_f32 v18, vcc, 1.0, v24, 1.0
	v_mul_f32_e32 v19, v18, v17
	v_fma_f32 v20, -v16, v19, v18
	v_fmac_f32_e32 v19, v20, v17
	v_fma_f32 v16, -v16, v19, v18
	v_div_fmas_f32 v16, v16, v17, v19
	v_lshlrev_b64 v[18:19], 11, v[68:69]
	v_div_fixup_f32 v16, v16, v24, 1.0
	v_lshl_add_u64 v[18:19], s[4:5], 0, v[18:19]
	v_lshl_add_u64 v[18:19], v[18:19], 0, s[6:7]
	v_pk_mul_f32 v[12:13], v[12:13], v[16:17] op_sel_hi:[1,0]
	v_pk_mul_f32 v[14:15], v[14:15], v[16:17] op_sel_hi:[1,0]
	v_pk_mul_f32 v[8:9], v[8:9], v[16:17] op_sel_hi:[1,0]
	v_pk_mul_f32 v[10:11], v[10:11], v[16:17] op_sel_hi:[1,0]
	v_pk_mul_f32 v[4:5], v[16:17], v[4:5] op_sel_hi:[0,1]
	v_pk_mul_f32 v[6:7], v[16:17], v[6:7] op_sel_hi:[0,1]
	v_pk_mul_f32 v[0:1], v[16:17], v[0:1] op_sel_hi:[0,1]
	v_pk_mul_f32 v[2:3], v[16:17], v[2:3] op_sel_hi:[0,1]
	v_lshl_add_u64 v[18:19], v[18:19], 0, v[66:67]
	v_cvt_pk_bf16_f32 v12, v12, v13
	v_cvt_pk_bf16_f32 v13, v14, v15
	v_cvt_pk_bf16_f32 v8, v8, v9
	v_cvt_pk_bf16_f32 v9, v10, v11
	v_cvt_pk_bf16_f32 v4, v4, v5
	v_cvt_pk_bf16_f32 v5, v6, v7
	v_cvt_pk_bf16_f32 v0, v0, v1
	v_cvt_pk_bf16_f32 v1, v2, v3
	flat_store_dwordx2 v[18:19], v[12:13]
	flat_store_dwordx2 v[18:19], v[8:9] offset:32
	flat_store_dwordx2 v[18:19], v[4:5] offset:64
	flat_store_dwordx2 v[18:19], v[0:1] offset:96
	s_waitcnt lgkmcnt(0)
	s_add_i32 s6, s71, 8
	s_cmp_gt_i32 s71, 23
	s_mov_b32 s71, s6
	s_cbranch_scc0 .LBB0_132
	s_branch .LBB0_81
